# MLA compute block: 6-deep ring with one wait per two reads (25 waits, deeper LDS latency tolerance)
# speedup vs baseline: 1.0022x; 1.0022x over previous
.LBB0_1483:
	s_add_i32 s53, s53, 1
	ds_read_b128 v[212:215], v165
	ds_read_b128 v[216:219], v165 offset:64
	ds_read_b128 v[220:223], v165 offset:128
	ds_read_b128 v[224:227], v165 offset:3584
	ds_read_b128 v[228:231], v165 offset:3648
	ds_read_b128 v[44:47], v165 offset:3712
	s_waitcnt lgkmcnt(4)
	v_mfma_f32_16x16x32_bf16 v[232:235], v[212:215], v[0:3], 0
	v_mfma_f32_16x16x32_bf16 v[240:243], v[212:215], v[12:15], 0
	ds_read_b128 v[212:215], v165 offset:7168
	v_mfma_f32_16x16x32_bf16 v[232:235], v[216:219], v[4:7], v[232:235]
	v_mfma_f32_16x16x32_bf16 v[240:243], v[216:219], v[16:19], v[240:243]
	ds_read_b128 v[216:219], v165 offset:7232
	s_waitcnt lgkmcnt(4)
	v_mfma_f32_16x16x32_bf16 v[232:235], v[220:223], v[8:11], v[232:235]
	v_mfma_f32_16x16x32_bf16 v[240:243], v[220:223], v[20:23], v[240:243]
	ds_read_b128 v[220:223], v165 offset:7296
	v_mfma_f32_16x16x32_bf16 v[236:239], v[224:227], v[0:3], 0
	v_mfma_f32_16x16x32_bf16 v[244:247], v[224:227], v[12:15], 0
	ds_read_b128 v[224:227], v165 offset:10752
	s_waitcnt lgkmcnt(4)
	v_mfma_f32_16x16x32_bf16 v[236:239], v[228:231], v[4:7], v[236:239]
	v_mfma_f32_16x16x32_bf16 v[244:247], v[228:231], v[16:19], v[244:247]
	ds_read_b128 v[228:231], v165 offset:10816
	v_mfma_f32_16x16x32_bf16 v[236:239], v[44:47], v[8:11], v[236:239]
	v_exp_f32_e32 v232, v232
	v_mfma_f32_16x16x32_bf16 v[244:247], v[44:47], v[20:23], v[244:247]
	v_exp_f32_e32 v233, v233
	ds_read_b128 v[44:47], v165 offset:10880
	s_waitcnt lgkmcnt(4)
	v_mfma_f32_16x16x32_bf16 v[168:171], v[212:215], v[0:3], 0
	v_exp_f32_e32 v234, v234
	v_mfma_f32_16x16x32_bf16 v[176:179], v[212:215], v[12:15], 0
	v_exp_f32_e32 v235, v235
	ds_read_b128 v[212:215], v160 offset:28672
	v_mfma_f32_16x16x32_bf16 v[168:171], v[216:219], v[4:7], v[168:171]
	v_cvt_pk_bf16_f32 v232, v232, v233
	v_cvt_pk_bf16_f32 v233, v234, v235
	v_mfma_f32_16x16x32_bf16 v[176:179], v[216:219], v[16:19], v[176:179]
	v_exp_f32_e32 v240, v240
	ds_read_b128 v[216:219], v160 offset:33280
	s_waitcnt lgkmcnt(4)
	v_mfma_f32_16x16x32_bf16 v[168:171], v[220:223], v[8:11], v[168:171]
	v_exp_f32_e32 v241, v241
	v_mfma_f32_16x16x32_bf16 v[176:179], v[220:223], v[20:23], v[176:179]
	v_exp_f32_e32 v242, v242
	ds_read_b128 v[220:223], v160 offset:37888
	v_mfma_f32_16x16x32_bf16 v[172:175], v[224:227], v[0:3], 0
	v_exp_f32_e32 v243, v243
	v_mfma_f32_16x16x32_bf16 v[108:111], v[224:227], v[12:15], 0
	v_cvt_pk_bf16_f32 v240, v240, v241
	v_cvt_pk_bf16_f32 v241, v242, v243
	ds_read_b128 v[224:227], v160 offset:42496
	s_waitcnt lgkmcnt(4)
	v_mfma_f32_16x16x32_bf16 v[172:175], v[228:231], v[4:7], v[172:175]
	v_exp_f32_e32 v236, v236
	v_mfma_f32_16x16x32_bf16 v[108:111], v[228:231], v[16:19], v[108:111]
	v_exp_f32_e32 v237, v237
	ds_read_b128 v[228:231], v160 offset:47104
	v_mfma_f32_16x16x32_bf16 v[172:175], v[44:47], v[8:11], v[172:175]
	v_exp_f32_e32 v238, v238
	v_mfma_f32_16x16x32_bf16 v[108:111], v[44:47], v[20:23], v[108:111]
	v_exp_f32_e32 v239, v239
	ds_read_b128 v[44:47], v165 offset:14336
	s_waitcnt lgkmcnt(4)
	v_cvt_pk_bf16_f32 v234, v236, v237
	v_cvt_pk_bf16_f32 v235, v238, v239
	v_exp_f32_e32 v244, v244
	v_exp_f32_e32 v245, v245
	v_mfma_f32_16x16x32_bf16 v[84:87], v[212:215], v[232:235], v[84:87]
	v_exp_f32_e32 v246, v246
	v_exp_f32_e32 v247, v247
	v_cvt_pk_bf16_f32 v242, v244, v245
	v_cvt_pk_bf16_f32 v243, v246, v247
	v_exp_f32_e32 v168, v168
	v_exp_f32_e32 v169, v169
	v_mfma_f32_16x16x32_bf16 v[68:71], v[212:215], v[240:243], v[68:71]
	v_exp_f32_e32 v170, v170
	ds_read_b128 v[212:215], v165 offset:14400
	v_mfma_f32_16x16x32_bf16 v[88:91], v[216:219], v[232:235], v[88:91]
	v_exp_f32_e32 v171, v171
	v_mfma_f32_16x16x32_bf16 v[72:75], v[216:219], v[240:243], v[72:75]
	v_cvt_pk_bf16_f32 v168, v168, v169
	v_cvt_pk_bf16_f32 v169, v170, v171
	ds_read_b128 v[216:219], v165 offset:14464
	s_waitcnt lgkmcnt(4)
	v_mfma_f32_16x16x32_bf16 v[92:95], v[220:223], v[232:235], v[92:95]
	v_exp_f32_e32 v176, v176
	v_mfma_f32_16x16x32_bf16 v[76:79], v[220:223], v[240:243], v[76:79]
	v_exp_f32_e32 v177, v177
	ds_read_b128 v[220:223], v165 offset:17920
	v_mfma_f32_16x16x32_bf16 v[96:99], v[224:227], v[232:235], v[96:99]
	v_exp_f32_e32 v178, v178
	v_mfma_f32_16x16x32_bf16 v[80:83], v[224:227], v[240:243], v[80:83]
	v_exp_f32_e32 v179, v179
	ds_read_b128 v[224:227], v165 offset:17984
	s_waitcnt lgkmcnt(4)
	v_mfma_f32_16x16x32_bf16 v[104:107], v[228:231], v[232:235], v[104:107]
	v_cvt_pk_bf16_f32 v176, v176, v177
	v_cvt_pk_bf16_f32 v177, v178, v179
	v_mfma_f32_16x16x32_bf16 v[100:103], v[228:231], v[240:243], v[100:103]
	v_exp_f32_e32 v172, v172
	ds_read_b128 v[228:231], v165 offset:18048
	v_mfma_f32_16x16x32_bf16 v[232:235], v[44:47], v[0:3], 0
	v_exp_f32_e32 v173, v173
	v_mfma_f32_16x16x32_bf16 v[240:243], v[44:47], v[12:15], 0
	v_exp_f32_e32 v174, v174
	ds_read_b128 v[44:47], v160 offset:28736
	s_waitcnt lgkmcnt(4)
	v_mfma_f32_16x16x32_bf16 v[232:235], v[212:215], v[4:7], v[232:235]
	v_exp_f32_e32 v175, v175
	v_mfma_f32_16x16x32_bf16 v[240:243], v[212:215], v[16:19], v[240:243]
	v_cvt_pk_bf16_f32 v170, v172, v173
	v_cvt_pk_bf16_f32 v171, v174, v175
	ds_read_b128 v[212:215], v160 offset:33344
	v_mfma_f32_16x16x32_bf16 v[232:235], v[216:219], v[8:11], v[232:235]
	v_exp_f32_e32 v108, v108
	v_mfma_f32_16x16x32_bf16 v[240:243], v[216:219], v[20:23], v[240:243]
	v_exp_f32_e32 v109, v109
	ds_read_b128 v[216:219], v160 offset:37952
	s_waitcnt lgkmcnt(4)
	v_mfma_f32_16x16x32_bf16 v[236:239], v[220:223], v[0:3], 0
	v_exp_f32_e32 v110, v110
	v_mfma_f32_16x16x32_bf16 v[244:247], v[220:223], v[12:15], 0
	v_exp_f32_e32 v111, v111
	ds_read_b128 v[220:223], v160 offset:42560
	v_mfma_f32_16x16x32_bf16 v[236:239], v[224:227], v[4:7], v[236:239]
	v_cvt_pk_bf16_f32 v178, v108, v109
	v_cvt_pk_bf16_f32 v179, v110, v111
	v_mfma_f32_16x16x32_bf16 v[244:247], v[224:227], v[16:19], v[244:247]
	v_exp_f32_e32 v232, v232
	ds_read_b128 v[224:227], v160 offset:47168
	s_waitcnt lgkmcnt(4)
	v_mfma_f32_16x16x32_bf16 v[236:239], v[228:231], v[8:11], v[236:239]
	v_exp_f32_e32 v233, v233
	v_mfma_f32_16x16x32_bf16 v[244:247], v[228:231], v[20:23], v[244:247]
	v_exp_f32_e32 v234, v234
	ds_read_b128 v[228:231], v165 offset:21504
	v_mfma_f32_16x16x32_bf16 v[84:87], v[44:47], v[168:171], v[84:87]
	v_exp_f32_e32 v235, v235
	v_mfma_f32_16x16x32_bf16 v[68:71], v[44:47], v[176:179], v[68:71]
	v_cvt_pk_bf16_f32 v232, v232, v233
	v_cvt_pk_bf16_f32 v233, v234, v235
	ds_read_b128 v[44:47], v165 offset:21568
	s_waitcnt lgkmcnt(4)
	v_mfma_f32_16x16x32_bf16 v[88:91], v[212:215], v[168:171], v[88:91]
	v_exp_f32_e32 v240, v240
	v_mfma_f32_16x16x32_bf16 v[72:75], v[212:215], v[176:179], v[72:75]
	v_exp_f32_e32 v241, v241
	ds_read_b128 v[212:215], v165 offset:21632
	v_mfma_f32_16x16x32_bf16 v[92:95], v[216:219], v[168:171], v[92:95]
	v_exp_f32_e32 v242, v242
	v_mfma_f32_16x16x32_bf16 v[76:79], v[216:219], v[176:179], v[76:79]
	v_exp_f32_e32 v243, v243
	ds_read_b128 v[216:219], v165 offset:25088
	s_waitcnt lgkmcnt(4)
	v_mfma_f32_16x16x32_bf16 v[96:99], v[220:223], v[168:171], v[96:99]
	v_cvt_pk_bf16_f32 v240, v240, v241
	v_cvt_pk_bf16_f32 v241, v242, v243
	v_mfma_f32_16x16x32_bf16 v[80:83], v[220:223], v[176:179], v[80:83]
	v_exp_f32_e32 v236, v236
	ds_read_b128 v[220:223], v165 offset:25152
	v_mfma_f32_16x16x32_bf16 v[104:107], v[224:227], v[168:171], v[104:107]
	v_exp_f32_e32 v237, v237
	v_mfma_f32_16x16x32_bf16 v[100:103], v[224:227], v[176:179], v[100:103]
	v_exp_f32_e32 v238, v238
	ds_read_b128 v[224:227], v165 offset:25216
	s_waitcnt lgkmcnt(4)
	v_mfma_f32_16x16x32_bf16 v[168:171], v[228:231], v[0:3], 0
	v_exp_f32_e32 v239, v239
	v_mfma_f32_16x16x32_bf16 v[176:179], v[228:231], v[12:15], 0
	v_cvt_pk_bf16_f32 v234, v236, v237
	v_cvt_pk_bf16_f32 v235, v238, v239
	ds_read_b128 v[228:231], v160 offset:28800
	v_mfma_f32_16x16x32_bf16 v[168:171], v[44:47], v[4:7], v[168:171]
	v_exp_f32_e32 v244, v244
	v_mfma_f32_16x16x32_bf16 v[176:179], v[44:47], v[16:19], v[176:179]
	v_exp_f32_e32 v245, v245
	ds_read_b128 v[44:47], v160 offset:33408
	s_waitcnt lgkmcnt(4)
	v_mfma_f32_16x16x32_bf16 v[168:171], v[212:215], v[8:11], v[168:171]
	v_exp_f32_e32 v246, v246
	v_mfma_f32_16x16x32_bf16 v[176:179], v[212:215], v[20:23], v[176:179]
	v_exp_f32_e32 v247, v247
	ds_read_b128 v[212:215], v160 offset:38016
	v_mfma_f32_16x16x32_bf16 v[172:175], v[216:219], v[0:3], 0
	v_cvt_pk_bf16_f32 v242, v244, v245
	v_cvt_pk_bf16_f32 v243, v246, v247
	v_mfma_f32_16x16x32_bf16 v[108:111], v[216:219], v[12:15], 0
	ds_read_b128 v[216:219], v160 offset:42624
	s_waitcnt lgkmcnt(4)
	v_mfma_f32_16x16x32_bf16 v[172:175], v[220:223], v[4:7], v[172:175]
	v_exp_f32_e32 v168, v168
	v_mfma_f32_16x16x32_bf16 v[108:111], v[220:223], v[16:19], v[108:111]
	v_exp_f32_e32 v169, v169
	ds_read_b128 v[220:223], v160 offset:47232
	v_mfma_f32_16x16x32_bf16 v[172:175], v[224:227], v[8:11], v[172:175]
	v_exp_f32_e32 v170, v170
	v_mfma_f32_16x16x32_bf16 v[108:111], v[224:227], v[20:23], v[108:111]
	v_exp_f32_e32 v171, v171
	ds_read_b128 v[224:227], v160 offset:28864
	s_waitcnt lgkmcnt(4)
	v_mfma_f32_16x16x32_bf16 v[84:87], v[228:231], v[232:235], v[84:87]
	v_cvt_pk_bf16_f32 v168, v168, v169
	v_cvt_pk_bf16_f32 v169, v170, v171
	v_mfma_f32_16x16x32_bf16 v[68:71], v[228:231], v[240:243], v[68:71]
	v_exp_f32_e32 v176, v176
	ds_read_b128 v[228:231], v160 offset:33472
	v_mfma_f32_16x16x32_bf16 v[88:91], v[44:47], v[232:235], v[88:91]
	v_exp_f32_e32 v177, v177
	v_mfma_f32_16x16x32_bf16 v[72:75], v[44:47], v[240:243], v[72:75]
	v_exp_f32_e32 v178, v178
	ds_read_b128 v[44:47], v160 offset:38080
	s_waitcnt lgkmcnt(4)
	v_mfma_f32_16x16x32_bf16 v[92:95], v[212:215], v[232:235], v[92:95]
	v_exp_f32_e32 v179, v179
	v_mfma_f32_16x16x32_bf16 v[76:79], v[212:215], v[240:243], v[76:79]
	v_cvt_pk_bf16_f32 v176, v176, v177
	v_cvt_pk_bf16_f32 v177, v178, v179
	ds_read_b128 v[212:215], v160 offset:42688
	v_mfma_f32_16x16x32_bf16 v[96:99], v[216:219], v[232:235], v[96:99]
	v_exp_f32_e32 v172, v172
	v_mfma_f32_16x16x32_bf16 v[80:83], v[216:219], v[240:243], v[80:83]
	v_exp_f32_e32 v173, v173
	ds_read_b128 v[216:219], v160 offset:47296
	s_waitcnt lgkmcnt(5)
	v_mfma_f32_16x16x32_bf16 v[104:107], v[220:223], v[232:235], v[104:107]
	v_exp_f32_e32 v174, v174
	v_mfma_f32_16x16x32_bf16 v[100:103], v[220:223], v[240:243], v[100:103]
	v_exp_f32_e32 v175, v175
	s_waitcnt lgkmcnt(4)
	v_cvt_pk_bf16_f32 v170, v172, v173
	v_cvt_pk_bf16_f32 v171, v174, v175
	v_exp_f32_e32 v108, v108
	v_exp_f32_e32 v109, v109
	v_mfma_f32_16x16x32_bf16 v[84:87], v[224:227], v[168:171], v[84:87]
	v_exp_f32_e32 v110, v110
	s_waitcnt lgkmcnt(3)
	v_mfma_f32_16x16x32_bf16 v[88:91], v[228:231], v[168:171], v[88:91]
	v_exp_f32_e32 v111, v111
	s_waitcnt lgkmcnt(2)
	v_mfma_f32_16x16x32_bf16 v[92:95], v[44:47], v[168:171], v[92:95]
	v_cvt_pk_bf16_f32 v178, v108, v109
	v_cvt_pk_bf16_f32 v179, v110, v111
	s_waitcnt lgkmcnt(1)
	v_mfma_f32_16x16x32_bf16 v[96:99], v[212:215], v[168:171], v[96:99]
	s_waitcnt lgkmcnt(0)
	v_mfma_f32_16x16x32_bf16 v[104:107], v[216:219], v[168:171], v[104:107]
	v_mfma_f32_16x16x32_bf16 v[68:71], v[224:227], v[176:179], v[68:71]
	v_mfma_f32_16x16x32_bf16 v[72:75], v[228:231], v[176:179], v[72:75]
	v_mfma_f32_16x16x32_bf16 v[76:79], v[44:47], v[176:179], v[76:79]
	v_mfma_f32_16x16x32_bf16 v[80:83], v[212:215], v[176:179], v[80:83]
	v_mfma_f32_16x16x32_bf16 v[100:103], v[216:219], v[176:179], v[100:103]
	s_cmp_eq_u32 s53, 34
	s_cbranch_scc1 .LBB0_1504
